# work-queue index for the next unit fetched when a unit starts (indexer and attention phases), on top of the de-serialised epilogues
# baseline (speedup 1.0000x reference)
; #define LAS __attribute__((address_space(3)))
; __device__ __forceinline__ int lane_now() { int l; asm volatile("v_mbcnt_lo_u32_b32 %0, -1, 0\n\tv_mbcnt_hi_u32_b32 %0, -1, %0" : "=v"(l)); return l; }
; __device__ __forceinline__ void run(Frame& F, int qword) {
;     const int wid = F.wave;
;     LAS unsigned char* lds = F.lds;
;     unsigned* qctr = (unsigned*)(F.ws + WS_CTL) + qword;
;     volatile LAS unsigned* uw = (volatile LAS unsigned*)(F.lds + MISC_OFF) + 20;
;     const bf16* QIH = WSP(bf16, WS_QIH); const bf16* KIH = WSP(bf16, WS_KIH);
;     const float* WI = WSP(float, WS_WI); unsigned* MASK = WSP(unsigned, WS_MASK);
;     LAS unsigned* TR = (LAS unsigned*)lds;
;     for (;;) {
;         __syncthreads();
;         if (wid == 0 && lane_now() == 0) *uw = __hip_atomic_fetch_add(qctr, 1u, __ATOMIC_RELAXED, __HIP_MEMORY_SCOPE_AGENT);
;         __syncthreads();
;         const unsigned un = __builtin_amdgcn_readfirstlane(*uw);
.LBB0_946:
	s_add_u32 s24, s42, 0x6200000
	s_addc_u32 s25, s43, 0
	s_add_u32 s26, s42, 0x5200000
	s_addc_u32 s27, s43, 0
	s_add_u32 s30, s42, 0x5100000
	s_addc_u32 s31, s43, 0
	s_add_u32 s46, s42, 0x4900000
	s_addc_u32 s47, s43, 0
	v_readlane_b32 s2, v254, 0
	s_cmp_lt_u32 s2, 64
	s_cselect_b64 s[0:1], -1, 0
	s_and_b32 s48, s2, 0xffffffc0
	s_lshl_b32 s2, s93, 13
	s_add_i32 s49, s2, 0
	s_add_i32 s50, s49, 0x9000
	s_lshl_b32 s51, s93, 2
	s_mul_i32 s2, s93, 0x2010
	s_waitcnt vmcnt(0)
	v_cndmask_b32_e64 v0, 0, 1, s[0:1]
	s_add_i32 s54, 0, 0x20190
	s_mov_b32 s35, 0
	s_add_i32 s52, s49, s2
	s_add_i32 s53, s51, 0xffffff01
	v_cmp_ne_u32_e64 s[2:3], 1, v0
	v_mov_b32_e32 v81, 0
	v_mov_b32_e32 v134, s54
	s_movk_i32 s55, 0x210
	s_mov_b64 s[36:37], 0x60
	s_movk_i32 s56, 0x100
	s_movk_i32 s57, 0x101
	v_mov_b32_e32 v135, 0x380
	s_add_i32 s58, s50, 0x400
	s_add_i32 s59, s50, 0x800
	s_add_i32 s60, s50, 0xc00
	s_and_b64 vcc, exec, s[2:3]
	s_cbranch_vccnz .Lqp2_skip0
	s_mov_b64 s[4:5], exec
	s_mov_b64 exec, 1
	v_mov_b32_e32 v255, 1
	global_atomic_add v255, v81, v255, s[42:43] offset:256 sc0
	s_mov_b64 exec, s[4:5]
.Lqp2_skip0:
	s_branch .LBB0_950
.LBB0_947:
	s_or_b64 exec, exec, s[0:1]

; __device__ __forceinline__ int lane_now() { int l; asm volatile("v_mbcnt_lo_u32_b32 %0, -1, 0\n\tv_mbcnt_hi_u32_b32 %0, -1, %0" : "=v"(l)); return l; }
; __device__ __forceinline__ void run(Frame& F, int qword) {
;     ...
;     for (;;) {
;         __syncthreads();
;         if (wid == 0 && lane_now() == 0) *uw = __hip_atomic_fetch_add(qctr, 1u, __ATOMIC_RELAXED, __HIP_MEMORY_SCOPE_AGENT);
;         __syncthreads();
;         const unsigned un = __builtin_amdgcn_readfirstlane(*uw);
.LBB0_950:
	s_and_b64 vcc, exec, s[2:3]
	s_barrier
	s_cbranch_vccnz .LBB0_956
	v_mbcnt_lo_u32_b32 v0, -1, 0
	v_mbcnt_hi_u32_b32 v0, -1, v0
	s_nop 0
	v_cmp_eq_u32_e32 vcc, 0, v0
	s_and_saveexec_b64 s[0:1], vcc
	s_cbranch_execz .LBB0_955
	s_mov_b64 s[6:7], exec
	v_mbcnt_lo_u32_b32 v0, s6, 0
	v_mbcnt_hi_u32_b32 v0, s7, v0
	v_cmp_eq_u32_e32 vcc, 0, v0
	s_and_saveexec_b64 s[4:5], vcc
	s_cbranch_execz .LBB0_954
	s_waitcnt vmcnt(0)
	v_mov_b32_e32 v1, v255

; #define LAS __attribute__((address_space(3)))
; __device__ __forceinline__ int lane_now() { int l; asm volatile("v_mbcnt_lo_u32_b32 %0, -1, 0\n\tv_mbcnt_hi_u32_b32 %0, -1, %0" : "=v"(l)); return l; }
; #define IDX_DMA_K(zo) do { _Pragma("unroll") for (int d0_ = 0; d0_ < 4; ++d0_) attn_body::glds16(kbh + (zo) + d0_ * 16, (unsigned)__builtin_amdgcn_readfirstlane(kdst + d0_ * 1024)); } while (0)
; __device__ __forceinline__ void run(Frame& F, int qword) {
;     ...
;         const unsigned un = __builtin_amdgcn_readfirstlane(*uw);
;         if (un >= 1024u) break;
;         int b, qg;
;         if (un < 896u) { qg = 63 - (int)(un >> 4); b = (int)(un & 15u); } else { qg = (int)((un - 896u) >> 4); b = (int)(un & 15u); }
;         int lane = lane_now(); asm volatile("" : "+v"(lane));
;         const int r32 = lane & 31, hi = lane >> 5;
;         const int tid = wid * 64 + lane;
;         int widv = wid; asm volatile("" : "+s"(widv));
;         const int unit = b * 64 + qg;
;         const size_t tok0 = (size_t)b * SEQ + 32 * qg;
;         unsigned* mrow = MASK + (size_t)unit * 2048;
;         const int ktmax = qg | 7;
;         if (qg < 8) {
; #pragma unroll
;             for (int i = 0; i < 8; ++i) { const int kt = widv + 8 * i; if (kt <= ktmax && hi == 0) mrow[kt * 32 + r32] = kt < qg ? 0xffffffffu : (kt == qg ? ((2u << r32) - 1u) : 0u); }
;             continue;
;         }
; #pragma unroll
;         for (int it = 0; it < 2; ++it) { const int rem = tid + 512 * it, row = rem >> 5, ch = rem & 31;
;             const v4u v = *(const v4u*)(QIH + (tok0 + row) * 256 + ch * 8);
;             *(LAS v4u*)(lds + row * QROW + ch * 16) = v; }
;         const f32x4 w4 = *(const f32x4*)(WI + (tok0 + r32) * 4);
;         __syncthreads();
;         unsigned sc[8][16];
;         const bf16* kbh = KIH + ((size_t)b * SEQ + r32) * 64 + hi * 8;
;         const LAS unsigned char* kbuf = lds + KBUF_OFF + wid * 8192 + lane * 16;
;         const unsigned kdst = (unsigned)(uintptr_t)(lds + KBUF_OFF + wid * 8192);
;     ...
;         if (widv <= qg) { int zoff = widv * 2048; asm volatile("" : "+v"(zoff)); IDX_DMA_K(zoff); }
.LBB0_956:
	s_waitcnt lgkmcnt(0)
	s_barrier
	ds_read_b32 v0, v134
	s_mov_b64 s[0:1], -1
	s_waitcnt lgkmcnt(0)
	v_readfirstlane_b32 s4, v0
	s_cmpk_gt_u32 s4, 0x3ff
	s_cbranch_scc1 .LBB0_949
	s_and_b64 vcc, exec, s[2:3]
	s_cbranch_vccnz .Lqp2_skip1
	s_mov_b64 s[0:1], exec
	s_mov_b64 exec, 1
	v_mov_b32_e32 v255, 1
	global_atomic_add v255, v81, v255, s[42:43] offset:256 sc0
	s_mov_b64 exec, s[0:1]
.Lqp2_skip1:
	v_sub_co_u32_e32 v0, vcc, s4, v135
	s_lshr_b32 s0, s4, 4
	s_sub_i32 s5, 63, s0
	v_readfirstlane_b32 s0, v0
	s_lshr_b32 s6, s0, 4
	s_and_b64 s[0:1], vcc, exec
	s_cselect_b32 s61, s5, s6
	s_and_b32 s4, s4, 15
	s_lshl_b32 s0, s4, 6
	s_add_i32 s34, s61, s0
	s_lshl_b64 s[0:1], s[34:35], 13
	s_add_u32 s38, s46, s0
	v_mbcnt_lo_u32_b32 v136, -1, 0
	v_mbcnt_hi_u32_b32 v136, -1, v136
	s_addc_u32 s39, s47, s1
	s_or_b32 s63, s61, 7
	s_mov_b32 s62, s93
	v_and_b32_e32 v137, 31, v136
	s_cmp_lt_u32 s61, 8
	s_mov_b64 s[0:1], -1
	s_cbranch_scc1 .LBB0_1290
	v_add_u32_e32 v4, s48, v136
	v_ashrrev_i32_e32 v10, 5, v4
	v_add_u32_e32 v4, 0x200, v4
	s_lshl_b32 s12, s61, 5
	s_lshl_b32 s0, s4, 11
	v_ashrrev_i32_e32 v12, 5, v4
	s_add_i32 s34, s12, s0
	v_ashrrev_i32_e32 v11, 31, v10
	v_ashrrev_i32_e32 v13, 31, v12
	v_lshlrev_b32_e32 v80, 4, v137
	v_lshl_add_u64 v[2:3], v[10:11], 0, s[34:35]
	v_lshl_add_u64 v[4:5], v[12:13], 0, s[34:35]
	v_lshl_add_u64 v[0:1], s[24:25], 0, v[80:81]
	v_lshlrev_b64 v[2:3], 9, v[2:3]
	v_lshlrev_b64 v[4:5], 9, v[4:5]
	v_lshl_add_u64 v[2:3], v[0:1], 0, v[2:3]
	v_lshl_add_u64 v[0:1], v[0:1], 0, v[4:5]
	global_load_dwordx4 v[2:5], v[2:3], off
	s_nop 0
	global_load_dwordx4 v[6:9], v[0:1], off
	v_add_u32_e32 v0, 0, v80
	v_or_b32_e32 v80, s34, v137
	v_lshl_add_u64 v[14:15], v[80:81], 4, s[30:31]
	global_load_dwordx4 v[64:67], v[14:15], off
	v_ashrrev_i32_e32 v1, 5, v136
	v_or_b32_e32 v16, s0, v137
	v_lshlrev_b32_e32 v14, 3, v1
	v_mad_u64_u32 v[10:11], s[0:1], v10, s55, v[0:1]
	s_cmp_le_i32 s62, s61
	v_mad_u64_u32 v[12:13], s[0:1], v12, s55, v[0:1]
	v_lshlrev_b32_e32 v80, 7, v16
	v_ashrrev_i32_e32 v15, 31, v14
	s_cselect_b64 s[0:1], -1, 0
	v_lshl_add_u64 v[16:17], s[26:27], 0, v[80:81]
	s_and_b64 vcc, exec, s[0:1]
	v_lshl_add_u64 v[82:83], v[14:15], 1, v[16:17]
	s_waitcnt vmcnt(2)
	ds_write_b128 v10, v[2:5]
	s_waitcnt vmcnt(1)
	ds_write_b128 v12, v[6:9]
	s_waitcnt lgkmcnt(0)
	s_barrier
	s_cbranch_vccz .LBB0_960
	s_lshl_b32 s4, s62, 11
	v_mov_b32_e32 v2, s4
	s_nop 0
	v_ashrrev_i32_e32 v3, 31, v2
	v_lshl_add_u64 v[2:3], v[2:3], 1, v[82:83]
	s_mov_b32 s4, m0
	s_mov_b32 m0, s50
	s_nop 0
	global_load_lds_dwordx4 v[2:3], off
	s_mov_b32 m0, s4
	v_lshl_add_u64 v[4:5], v[2:3], 0, 32
	s_mov_b32 s4, m0
	s_mov_b32 m0, s58
	s_nop 0
	global_load_lds_dwordx4 v[4:5], off
	s_mov_b32 m0, s4
	v_lshl_add_u64 v[4:5], v[2:3], 0, 64
	s_mov_b32 s4, m0
	s_mov_b32 m0, s59
	s_nop 0
	global_load_lds_dwordx4 v[4:5], off
	s_mov_b32 m0, s4
	v_lshl_add_u64 v[2:3], v[2:3], 0, s[36:37]
	s_mov_b32 s4, m0
	s_mov_b32 m0, s60
	s_nop 0
	global_load_lds_dwordx4 v[2:3], off
	s_mov_b32 m0, s4

; __device__ __forceinline__ int lane_now() { int l; asm volatile("v_mbcnt_lo_u32_b32 %0, -1, 0\n\tv_mbcnt_hi_u32_b32 %0, -1, %0" : "=v"(l)); return l; }
; __device__ __forceinline__ void run(Frame& F, int qword) {
;     ...
;         else {
;             __syncthreads();
;             if ((F.wave * 64 + lane_now()) == 0) *uw = nstat * (unsigned)F.G + __hip_atomic_fetch_add(qctr, 1u, __ATOMIC_RELAXED, __HIP_MEMORY_SCOPE_AGENT);
;             __syncthreads();
;             un = __builtin_amdgcn_readfirstlane(*uw);
.LBB0_1381:
	s_cmp_eq_u32 s77, 0
	s_cselect_b64 s[0:1], -1, 0
	s_and_b64 s[0:1], s[6:7], s[0:1]
	s_and_b64 vcc, exec, s[0:1]
	s_mov_b32 s4, s96
	s_cbranch_vccnz .LBB0_1387
	s_waitcnt vmcnt(0) lgkmcnt(0)
	s_barrier
	v_mbcnt_lo_u32_b32 v0, -1, 0
	v_mbcnt_hi_u32_b32 v0, -1, v0
	s_nop 0
	v_sub_u32_e32 v0, 0, v0
	v_cmp_eq_u32_e32 vcc, s70, v0
	s_and_saveexec_b64 s[0:1], vcc
	s_cbranch_execz .LBB0_1386
	s_mov_b64 s[4:5], exec
	v_mbcnt_lo_u32_b32 v0, s4, 0
	v_mbcnt_hi_u32_b32 v0, s5, v0
	v_cmp_eq_u32_e32 vcc, 0, v0
	s_and_saveexec_b64 s[2:3], vcc
	s_cbranch_execz .LBB0_1385
	s_waitcnt vmcnt(0)
	v_mov_b32_e32 v2, v255

; __device__ __forceinline__ int lane_now() { int l; asm volatile("v_mbcnt_lo_u32_b32 %0, -1, 0\n\tv_mbcnt_hi_u32_b32 %0, -1, %0" : "=v"(l)); return l; }
; __device__ __forceinline__ void run(Frame& F, int qword) {
;     ...
;     for (unsigned it = 0;; ++it) {
;         unsigned un;
;         if (it < nstat) un = blockIdx.x;
;         else {
;             __syncthreads();
;             if ((F.wave * 64 + lane_now()) == 0) *uw = nstat * (unsigned)F.G + __hip_atomic_fetch_add(qctr, 1u, __ATOMIC_RELAXED, __HIP_MEMORY_SCOPE_AGENT);
;             __syncthreads();
;             un = __builtin_amdgcn_readfirstlane(*uw);
;         }
;         if (un >= (unsigned)NUNITS) break;
.LBB0_1388:
	s_cmp_lg_u32 s70, 0
	s_cbranch_scc1 .Lqp3_skip
	s_mov_b64 s[2:3], exec
	s_mov_b64 exec, 1
	v_mov_b32_e32 v255, 1
	global_atomic_add v255, v1, v255, s[42:43] offset:512 sc0
	s_mov_b64 exec, s[2:3]
